# MLA: one static s_setprio 1 for the late (staggered) wave half during the MLA units, back to 0 after
# speedup vs baseline: 1.0003x; 1.0003x over previous
.LBB0_1174:
	v_readfirstlane_b32 s64, v206
	s_nop 3
	s_lshr_b32 s64, s64, 8
	s_mov_b32 s66, 0
	s_mov_b32 s67, 0x8000
	s_cmp_eq_u32 s64, 0
	s_cbranch_scc1 .Lmla_prio_skip
	s_setprio 1

.LBB0_1225:
	s_setprio 0
	s_xor_b64 s[2:3], s[0:1], -1
	v_readlane_b32 s0, v252, 43
	s_add_i32 s51, s51, s0
	v_readlane_b32 s0, v252, 41
	v_readlane_b32 s1, v252, 42
	s_and_b64 s[0:1], s[0:1], exec
	s_cselect_b32 s18, s51, s50
	s_cmpk_lt_i32 s18, 0x1000
	s_cselect_b64 s[4:5], -1, 0
	v_cndmask_b32_e64 v0, 0, 1, s[4:5]
	s_mov_b64 s[0:1], -1
	s_and_b64 vcc, exec, s[2:3]
	v_cmp_ne_u32_e64 s[2:3], 1, v0
	s_cbranch_vccz .LBB0_1250
	v_writelane_b32 v255, s94, 2
	v_writelane_b32 v254, s18, 57
	s_mov_b32 s23, s49
	v_writelane_b32 v255, s95, 3
	v_writelane_b32 v255, s2, 4
	s_and_b64 vcc, exec, s[2:3]
	s_nop 0
	v_writelane_b32 v255, s3, 5
	s_cbranch_vccnz .LBB0_1249
	v_readlane_b32 s12, v255, 2
	v_readlane_b32 s13, v255, 3
	s_add_u32 s0, s12, 0x17600000
	v_writelane_b32 v255, s0, 6
	s_addc_u32 s0, s13, 0
	v_writelane_b32 v255, s0, 7
	s_add_u32 s0, s12, 0x19600000
	s_addc_u32 s1, s13, 0
	v_lshrrev_b32_e32 v5, 5, v158
	v_and_b32_e32 v6, 7, v160
	v_lshrrev_b32_e32 v8, 4, v158
	v_lshrrev_b32_e32 v13, 1, v158
	v_lshlrev_b32_e32 v9, 1, v158
	v_writelane_b32 v255, s0, 8
	v_lshlrev_b32_e32 v0, 4, v5
	v_mov_b32_e32 v1, v149
	v_bitop3_b32 v10, v8, v160, 7 bitop3:0x78
	v_bitop3_b32 v11, v8, v6, 4 bitop3:0x36
	v_bitop3_b32 v12, v8, v160, 3 bitop3:0x78
	v_and_b32_e32 v8, 19, v160
	v_and_b32_e32 v9, 8, v9
	v_and_b32_e32 v15, 4, v13
	v_writelane_b32 v255, s1, 9
	v_and_b32_e32 v162, 31, v160
	v_lshl_add_u64 v[2:3], s[12:13], 0, v[0:1]
	s_mov_b64 s[0:1], 0x15600000
	v_or3_b32 v8, v8, v9, v15
	v_lshl_add_u64 v[164:165], v[2:3], 0, s[0:1]
	v_or_b32_e32 v166, 32, v158
	v_cmp_gt_u32_e64 s[0:1], 16, v162
	v_lshlrev_b32_e32 v8, 10, v8
	v_mov_b32_e32 v9, v149
	v_lshlrev_b32_e32 v148, 3, v5
	v_writelane_b32 v254, s0, 34
	v_lshl_add_u64 v[8:9], s[12:13], 0, v[8:9]
	v_add_u32_e32 v16, -8, v166
	v_writelane_b32 v254, s1, 35
	v_lshl_add_u64 v[0:1], v[8:9], 0, v[0:1]
	s_mov_b64 s[0:1], 0xd4400
	v_min_u32_e32 v16, 48, v16
	v_or_b32_e32 v18, 32, v148
	v_lshl_add_u64 v[168:169], v[0:1], 0, s[0:1]
	s_mov_b64 s[0:1], 0xd8400
	v_sub_u32_e32 v17, v148, v16
	v_sub_u32_e32 v16, v18, v16
	v_lshl_add_u64 v[170:171], v[2:3], 0, s[0:1]
	v_sub_u32_e64 v8, v162, 8 clamp
	v_cmp_gt_u32_e64 s[0:1], 16, v16
	v_sub_u32_e32 v9, v148, v8
	v_add_u32_e32 v21, 1, v9
	v_writelane_b32 v254, s0, 41
	v_sub_u32_e32 v8, v18, v8
	v_cmp_gt_u32_e64 s[62:63], 16, v8
	v_writelane_b32 v254, s1, 42
	v_cmp_gt_u32_e64 s[0:1], 16, v9
	v_cmp_gt_u32_e64 s[64:65], 15, v8
	v_cmp_gt_u32_e64 s[66:67], 14, v8
	v_writelane_b32 v254, s0, 43
	v_cmp_gt_u32_e64 s[68:69], 13, v8
	v_cmp_gt_u32_e64 s[70:71], 12, v8
	v_writelane_b32 v254, s1, 44
	v_cmp_gt_u32_e64 s[0:1], 16, v21
	v_add_u32_e32 v21, 2, v9
	v_cmp_gt_u32_e64 s[72:73], 11, v8
	v_writelane_b32 v254, s0, 45
	v_cmp_gt_u32_e64 s[74:75], 10, v8
	v_add_u32_e32 v8, 1, v16
	v_writelane_b32 v254, s1, 46
	v_cmp_gt_u32_e64 s[0:1], 16, v21
	v_add_u32_e32 v21, 3, v9
	v_cmp_gt_u32_e64 s[76:77], 16, v8
	v_writelane_b32 v254, s0, 47
	v_add_u32_e32 v8, 2, v16
	v_cmp_gt_u32_e64 s[78:79], 16, v8
	v_writelane_b32 v254, s1, 48
	v_cmp_gt_u32_e64 s[0:1], 16, v21
	v_add_u32_e32 v21, 4, v9
	v_add_u32_e32 v8, 3, v16
	v_writelane_b32 v254, s0, 49
	v_cmp_gt_u32_e64 s[80:81], 16, v8
	v_add_u32_e32 v8, 4, v16
	v_writelane_b32 v254, s1, 50
	v_cmp_gt_u32_e64 s[0:1], 16, v21
	v_add_u32_e32 v21, 5, v9
	v_bfe_u32 v7, v160, 3, 2
	v_writelane_b32 v254, s0, 51
	v_lshrrev_b32_e32 v159, 2, v158
	v_and_or_b32 v4, v159, 8, v7
	v_writelane_b32 v254, s1, 52
	v_cmp_gt_u32_e64 s[0:1], 16, v21
	v_add_u32_e32 v21, 6, v9
	v_bfe_u32 v14, v158, 1, 3
	v_writelane_b32 v254, s0, 62
	v_bfe_u32 v1, v158, 2, 2
	v_lshlrev_b32_e32 v7, 10, v7
	v_writelane_b32 v254, s1, 63
	v_cmp_gt_u32_e64 s[0:1], 16, v21
	v_add_u32_e32 v21, 7, v9
	v_cmp_gt_u32_e64 s[26:27], 16, v21
	v_add_u32_e32 v21, 17, v9
	v_writelane_b32 v255, s0, 0
	v_cmp_gt_u32_e64 s[30:31], 16, v21
	v_add_u32_e32 v21, 18, v9
	v_writelane_b32 v255, s1, 1
	s_movk_i32 s0, 0xffef
	v_cmp_gt_u32_e64 s[34:35], 16, v21
	v_add_u32_e32 v21, 19, v9
	v_cmp_lt_u32_e64 s[8:9], s0, v9
	v_cmp_gt_u32_e64 s[36:37], 16, v21
	v_add_u32_e32 v21, 20, v9
	v_cmp_lt_u32_e64 s[46:47], s0, v17
	v_cmp_gt_u32_e64 s[0:1], 16, v8
	v_add_u32_e32 v8, 5, v16
	v_cmp_gt_u32_e64 s[38:39], 16, v21
	v_add_u32_e32 v21, 21, v9
	v_cmp_gt_u32_e64 s[2:3], 16, v8
	v_add_u32_e32 v8, 6, v16
	v_cmp_gt_u32_e64 s[40:41], 16, v21
	v_add_u32_e32 v21, 22, v9
	v_add_u32_e32 v9, 23, v9
	v_cmp_gt_u32_e64 s[4:5], 16, v8
	v_add_u32_e32 v8, 7, v16
	v_cmp_gt_u32_e64 s[44:45], 16, v9
	v_add_u32_e32 v9, 17, v17
	v_cmp_gt_u32_e64 s[82:83], 16, v8
	v_add_u32_e32 v8, 17, v16
	v_cmp_gt_u32_e64 s[48:49], 16, v9
	v_add_u32_e32 v9, 18, v17
	v_cmp_gt_u32_e64 s[86:87], 16, v8
	v_add_u32_e32 v8, 18, v16
	v_cmp_gt_u32_e64 s[50:51], 16, v9
	v_add_u32_e32 v9, 19, v17
	v_cmp_gt_u32_e64 s[88:89], 16, v8
	v_add_u32_e32 v8, 19, v16
	v_cmp_gt_u32_e64 s[52:53], 16, v9
	v_add_u32_e32 v9, 20, v17
	v_cmp_gt_u32_e64 s[90:91], 16, v8
	v_add_u32_e32 v8, 20, v16
	v_cmp_gt_u32_e64 s[54:55], 16, v9
	v_add_u32_e32 v9, 21, v17
	v_cmp_gt_u32_e64 s[92:93], 16, v8
	v_add_u32_e32 v8, 21, v16
	v_cmp_gt_u32_e64 s[56:57], 16, v9
	v_add_u32_e32 v9, 22, v17
	v_cmp_gt_u32_e64 s[94:95], 16, v8
	v_add_u32_e32 v8, 22, v16
	v_cmp_gt_u32_e64 s[58:59], 16, v9
	v_add_u32_e32 v9, 23, v17
	v_cmp_gt_u32_e64 s[96:97], 16, v8
	v_add_u32_e32 v8, 23, v16
	v_cmp_gt_u32_e64 s[60:61], 16, v9
	v_cmp_gt_u32_e64 s[6:7], 16, v8
	v_lshl_add_u64 v[8:9], s[12:13], 0, v[148:149]
	s_mov_b64 s[12:13], 0x5600000
	v_bitop3_b32 v13, v13, v5, 7 bitop3:0x6c
	v_bitop3_b32 v18, v5, v14, 2 bitop3:0x36
	v_bitop3_b32 v19, v5, v14, 4 bitop3:0x36
	v_bitop3_b32 v14, v5, v14, 6 bitop3:0x36
	v_bitop3_b32 v20, v159, v5, 3 bitop3:0x6c
	v_bitop3_b32 v1, v5, v1, 2 bitop3:0x36
	v_lshl_add_u64 v[172:173], v[8:9], 0, s[12:13]
	v_lshl_or_b32 v5, v5, 13, v7
	v_readlane_b32 s12, v254, 6
	v_lshl_or_b32 v148, v10, 4, v5
	v_readlane_b32 s13, v254, 7
	v_lshlrev_b32_e32 v7, 2, v166
	v_lshlrev_b32_e32 v4, 9, v4
	v_lshl_add_u64 v[174:175], s[12:13], 0, v[148:149]
	v_lshl_or_b32 v148, v11, 4, v5
	v_lshl_add_u64 v[176:177], s[12:13], 0, v[148:149]
	v_lshlrev_b32_e32 v148, 4, v12
	v_lshlrev_b32_e32 v6, 3, v12
	v_lshlrev_b32_e32 v0, 3, v10
	v_lshlrev_b32_e32 v2, 3, v11
	v_lshl_add_u32 v3, v162, 7, s33
	v_lshl_add_u32 v15, v162, 6, s33
	v_lshlrev_b32_e32 v13, 4, v13
	v_lshlrev_b32_e32 v18, 4, v18
	v_lshlrev_b32_e32 v19, 4, v19
	v_lshlrev_b32_e32 v14, 4, v14
	v_lshlrev_b32_e32 v20, 4, v20
	v_lshlrev_b32_e32 v1, 4, v1
	v_lshl_add_u64 v[178:179], s[12:13], 0, v[148:149]
	v_lshlrev_b32_e32 v5, 15, v159
	v_sub_u32_e32 v163, 0, v7
	v_lshlrev_b32_e32 v7, 2, v162
	v_readlane_b32 s12, v254, 57
	v_cmp_gt_u32_e64 s[42:43], 16, v21
	v_cmp_lt_u32_e64 s[84:85], 23, v16
	v_and_b32_e32 v161, 32, v158
	v_sub_u32_e32 v167, 0, v7
	v_lshlrev_b32_e32 v219, 1, v5
	v_lshlrev_b32_e32 v180, 1, v6
	v_lshlrev_b32_e32 v182, 1, v4
	v_lshlrev_b32_e32 v184, 1, v0
	v_lshlrev_b32_e32 v186, 1, v2
	s_add_i32 s14, s33, 0x2400
	s_add_i32 s15, s33, 0x2800
	s_add_i32 s16, s33, 0x3400
	s_add_i32 s17, s33, 0x3800
	s_add_i32 s18, s33, 0x3c00
	v_add_u32_e32 v220, v3, v13
	v_add_u32_e32 v221, v3, v18
	v_add_u32_e32 v222, v3, v19
	v_add_u32_e32 v223, v3, v14
	v_add_u32_e32 v224, v15, v20
	v_add_u32_e32 v225, v15, v1
	s_mov_b32 s24, s12
	s_mov_b32 s13, s12
	s_branch .LBB0_1229
